# forgetting-attention straight iteration with hand-scheduled half-steps: PV MFMAs lead, score-init subtracts in the first two MFMA gaps, exps in place, softmax VALU spread over the gaps
# baseline (speedup 1.0000x reference)
.LfB_688:
	s_or_b64 exec, exec, s[20:21]
	s_ashr_i32 s15, s14, 31
	s_lshl_b64 s[20:21], s[14:15], 13
	s_add_u32 s20, s95, s20
	s_addc_u32 s21, s96, s21
	s_add_u32 s20, s20, 0x1000
	s_addc_u32 s21, s21, 0
	v_mov_b32_e32 v153, v0
	global_load_dwordx4 v[132:135], v182, s[20:21] offset:2048
	s_add_i32 s15, s12, 0x100
	v_add_u32_e32 v1, s15, v148
	s_waitcnt lgkmcnt(0)
	v_add_u32_e32 v153, s92, v167
	ds_read_b64_tr_b16 v[2:3], v153
	ds_read_b64_tr_b16 v[4:5], v153 offset:1536
	ds_read_b64_tr_b16 v[6:7], v153 offset:64
	ds_read_b64_tr_b16 v[8:9], v153 offset:1600
	ds_read_b128 v[174:177], v1 offset:20704
	ds_read_b128 v[178:181], v1 offset:20672
	ds_read_b128 v[248:251], v1 offset:20640
	ds_read_b128 v[252:255], v1 offset:20608
	v_add_u32_e32 v1, s15, v162
	v_add_u32_e32 v10, v1, v163
	v_add_u32_e32 v14, v1, v164
	v_add_u32_e32 v15, v1, v165
	v_add_u32_e32 v1, v1, v166
	ds_read_b128 v[10:13], v10 offset:4096
	ds_read_b128 v[104:107], v14 offset:4096
	ds_read_b128 v[108:111], v15 offset:4096
	ds_read_b128 v[140:143], v1 offset:4096
	s_setprio 1
	s_waitcnt lgkmcnt(10)
	v_mfma_f32_32x32x16_bf16 v[50:65], v[2:5], v[96:99], v[50:65]
	s_waitcnt lgkmcnt(7)
	v_sub_f32_e32 v49, v95, v177
	v_sub_f32_e32 v48, v94, v176
	v_sub_f32_e32 v47, v93, v175
	v_sub_f32_e32 v46, v92, v174
	s_waitcnt lgkmcnt(6)
	v_sub_f32_e32 v45, v91, v181
	v_sub_f32_e32 v44, v90, v180
	v_sub_f32_e32 v43, v89, v179
	v_sub_f32_e32 v42, v88, v178
	v_mfma_f32_32x32x16_bf16 v[16:31], v[6:9], v[96:99], v[16:31]
	ds_read_b64_tr_b16 v[2:3], v153 offset:3072
	ds_read_b64_tr_b16 v[4:5], v153 offset:4608
	s_waitcnt lgkmcnt(7)
	v_sub_f32_e32 v41, v87, v251
	v_sub_f32_e32 v40, v86, v250
	v_sub_f32_e32 v39, v85, v249
	v_sub_f32_e32 v38, v84, v248
	s_waitcnt lgkmcnt(6)
	v_sub_f32_e32 v37, v83, v255
	v_sub_f32_e32 v36, v82, v254
	v_sub_f32_e32 v35, v33, v253
	v_sub_f32_e32 v34, v32, v252
	v_exp_f32_e32 v66, v66
	v_exp_f32_e32 v67, v67
	s_waitcnt lgkmcnt(5)
	v_mfma_f32_32x32x16_bf16 v[34:49], v[10:13], v[120:123], v[34:49]
	ds_read_b64_tr_b16 v[6:7], v153 offset:3136
	ds_read_b64_tr_b16 v[8:9], v153 offset:4672
	v_exp_f32_e32 v68, v68
	v_exp_f32_e32 v69, v69
	v_exp_f32_e32 v70, v70
	v_add_f32_e32 v160, v160, v66
	v_add_f32_e32 v160, v160, v67
	s_waitcnt lgkmcnt(2)
	v_mfma_f32_32x32x16_bf16 v[50:65], v[2:5], v[100:103], v[50:65]
	v_exp_f32_e32 v71, v71
	v_exp_f32_e32 v72, v72
	v_exp_f32_e32 v73, v73
	v_add_f32_e32 v160, v160, v68
	v_add_f32_e32 v160, v160, v69
	v_cvt_pk_bf16_f32 v96, v66, v67
	v_cvt_pk_bf16_f32 v97, v68, v69
	v_mfma_f32_32x32x16_bf16 v[34:49], v[104:107], v[112:115], v[34:49]
	v_exp_f32_e32 v74, v74
	v_exp_f32_e32 v75, v75
	v_exp_f32_e32 v76, v76
	v_add_f32_e32 v160, v160, v70
	v_add_f32_e32 v160, v160, v71
	v_add_f32_e32 v160, v160, v72
	v_cvt_pk_bf16_f32 v98, v70, v71
	s_waitcnt lgkmcnt(0)
	v_mfma_f32_32x32x16_bf16 v[16:31], v[6:9], v[100:103], v[16:31]
	v_exp_f32_e32 v77, v77
	v_exp_f32_e32 v78, v78
	v_exp_f32_e32 v79, v79
	v_add_f32_e32 v160, v160, v73
	v_add_f32_e32 v160, v160, v74
	v_add_f32_e32 v160, v160, v75
	v_cvt_pk_bf16_f32 v99, v72, v73
	v_mfma_f32_32x32x16_bf16 v[34:49], v[108:111], v[116:119], v[34:49]
	v_exp_f32_e32 v80, v80
	v_exp_f32_e32 v81, v81
	v_add_f32_e32 v160, v160, v76
	v_add_f32_e32 v160, v160, v77
	v_add_f32_e32 v160, v160, v78
	v_add_f32_e32 v160, v160, v79
	v_mfma_f32_32x32x16_bf16 v[34:49], v[140:143], v[124:127], v[34:49]
	v_add_f32_e32 v160, v160, v80
	v_add_f32_e32 v160, v160, v81
	v_cvt_pk_bf16_f32 v100, v74, v75
	v_cvt_pk_bf16_f32 v101, v76, v77
	v_cvt_pk_bf16_f32 v102, v78, v79
	v_cvt_pk_bf16_f32 v103, v80, v81
	s_setprio 0
	s_add_i32 s15, s97, 0x100
	v_add_u32_e32 v1, s15, v148
	s_waitcnt lgkmcnt(0)
	v_add_u32_e32 v153, s12, v168
	ds_read_b64_tr_b16 v[2:3], v153
	ds_read_b64_tr_b16 v[4:5], v153 offset:1536
	ds_read_b64_tr_b16 v[6:7], v153 offset:64
	ds_read_b64_tr_b16 v[8:9], v153 offset:1600
	ds_read_b128 v[174:177], v1 offset:20576
	ds_read_b128 v[178:181], v1 offset:20544
	ds_read_b128 v[248:251], v1 offset:20512
	ds_read_b128 v[252:255], v1 offset:20480
	v_add_u32_e32 v1, s15, v162
	v_add_u32_e32 v10, v1, v163
	v_add_u32_e32 v14, v1, v164
	v_add_u32_e32 v15, v1, v165
	v_add_u32_e32 v1, v1, v166
	ds_read_b128 v[10:13], v10
	ds_read_b128 v[104:107], v14
	ds_read_b128 v[108:111], v15
	ds_read_b128 v[140:143], v1
	s_setprio 1
	s_waitcnt lgkmcnt(10)
	v_mfma_f32_32x32x16_bf16 v[50:65], v[2:5], v[96:99], v[50:65]
	s_waitcnt lgkmcnt(7)
	v_sub_f32_e32 v81, v95, v177
	v_sub_f32_e32 v80, v94, v176
	v_sub_f32_e32 v79, v93, v175
	v_sub_f32_e32 v78, v92, v174
	s_waitcnt lgkmcnt(6)
	v_sub_f32_e32 v77, v91, v181
	v_sub_f32_e32 v76, v90, v180
	v_sub_f32_e32 v75, v89, v179
	v_sub_f32_e32 v74, v88, v178
	v_mfma_f32_32x32x16_bf16 v[16:31], v[6:9], v[96:99], v[16:31]
	ds_read_b64_tr_b16 v[2:3], v153 offset:3072
	ds_read_b64_tr_b16 v[4:5], v153 offset:4608
	s_waitcnt lgkmcnt(7)
	v_sub_f32_e32 v73, v87, v251
	v_sub_f32_e32 v72, v86, v250
	v_sub_f32_e32 v71, v85, v249
	v_sub_f32_e32 v70, v84, v248
	s_waitcnt lgkmcnt(6)
	v_sub_f32_e32 v69, v83, v255
	v_sub_f32_e32 v68, v82, v254
	v_sub_f32_e32 v67, v33, v253
	v_sub_f32_e32 v66, v32, v252
	v_exp_f32_e32 v34, v34
	v_exp_f32_e32 v35, v35
	s_waitcnt lgkmcnt(5)
	v_mfma_f32_32x32x16_bf16 v[66:81], v[10:13], v[120:123], v[66:81]
	ds_read_b64_tr_b16 v[6:7], v153 offset:3136
	ds_read_b64_tr_b16 v[8:9], v153 offset:4672
	v_exp_f32_e32 v36, v36
	v_exp_f32_e32 v37, v37
	v_exp_f32_e32 v38, v38
	v_add_f32_e32 v160, v160, v34
	v_add_f32_e32 v160, v160, v35
	s_waitcnt lgkmcnt(2)
	v_mfma_f32_32x32x16_bf16 v[50:65], v[2:5], v[100:103], v[50:65]
	v_exp_f32_e32 v39, v39
	v_exp_f32_e32 v40, v40
	v_exp_f32_e32 v41, v41
	v_add_f32_e32 v160, v160, v36
	v_add_f32_e32 v160, v160, v37
	v_cvt_pk_bf16_f32 v96, v34, v35
	v_cvt_pk_bf16_f32 v97, v36, v37
	v_mfma_f32_32x32x16_bf16 v[66:81], v[104:107], v[112:115], v[66:81]
	v_exp_f32_e32 v42, v42
	v_exp_f32_e32 v43, v43
	v_exp_f32_e32 v44, v44
	v_add_f32_e32 v160, v160, v38
	v_add_f32_e32 v160, v160, v39
	v_add_f32_e32 v160, v160, v40
	v_cvt_pk_bf16_f32 v98, v38, v39
	s_waitcnt lgkmcnt(0)
	v_mfma_f32_32x32x16_bf16 v[16:31], v[6:9], v[100:103], v[16:31]
	v_exp_f32_e32 v45, v45
	v_exp_f32_e32 v46, v46
	v_exp_f32_e32 v47, v47
	v_add_f32_e32 v160, v160, v41
	v_add_f32_e32 v160, v160, v42
	v_add_f32_e32 v160, v160, v43
	v_cvt_pk_bf16_f32 v99, v40, v41
	v_mfma_f32_32x32x16_bf16 v[66:81], v[108:111], v[116:119], v[66:81]
	v_exp_f32_e32 v48, v48
	v_exp_f32_e32 v49, v49
	v_add_f32_e32 v160, v160, v44
	v_add_f32_e32 v160, v160, v45
	v_add_f32_e32 v160, v160, v46
	v_add_f32_e32 v160, v160, v47
	v_mfma_f32_32x32x16_bf16 v[66:81], v[140:143], v[124:127], v[66:81]
	v_add_f32_e32 v160, v160, v48
	v_add_f32_e32 v160, v160, v49
	v_cvt_pk_bf16_f32 v100, v42, v43
	v_cvt_pk_bf16_f32 v101, v44, v45
	v_cvt_pk_bf16_f32 v102, v46, v47
	v_cvt_pk_bf16_f32 v103, v48, v49
	s_setprio 0
	s_add_i32 s15, s92, 0x100
	v_add_u32_e32 v1, s15, v159
	s_waitcnt vmcnt(0)
	ds_write_b128 v1, v[136:139]
	s_and_saveexec_b64 s[16:17], s[6:7]
	s_cbranch_execz .LfB_734
	s_mov_b32 s20, 0x3fb8aa3b
	v_add_u32_e32 v1, s15, v158
	s_waitcnt lgkmcnt(1)
	v_pk_mul_f32 v[4:5], v[130:131], s[20:21] op_sel_hi:[1,0]
	s_mov_b32 s90, 0x3fb8aa3b
	v_pk_mul_f32 v[2:3], v[128:129], s[20:21] op_sel_hi:[1,0]
	ds_write_b128 v1, v[2:5] offset:20480
